# mla_up epilogue: six one-dword touch loads per wave at the top bring the later row pairs' gate/partial lines towards L2 while the first pair is processed
# baseline (speedup 1.0000x reference)
; __device__ __forceinline__ float sigmoidf_(float g) { return __builtin_amdgcn_rcpf(1.f + __expf(-g)); }
; __device__ __forceinline__ u32x4 pack8(const f32x4& a, const f32x4& b) { u32x4 w; w.x = cvt_pk_bf16(a[0], a[1]); w.y = cvt_pk_bf16(a[2], a[3]); w.z = cvt_pk_bf16(b[0], b[1]); w.w = cvt_pk_bf16(b[2], b[3]); return w; }
; __device__ __forceinline__ void unpack8(const u32x4& w, float (&v)[8]) { v[0] = bf_lo(w.x); v[1] = bf_hi(w.x); v[2] = bf_lo(w.y); v[3] = bf_hi(w.y); v[4] = bf_lo(w.z); v[5] = bf_hi(w.z); v[6] = bf_lo(w.w); v[7] = bf_hi(w.w); }
;     __device__ __forceinline__ void apply(const Ld& d, int row, int c0, int, int, int, const f32x4& a0, const f32x4& b0, const f32x4& a1, const f32x4& b1) const { half(d.g0, row, c0, a0, b0); half(d.g1, row, c0 + 128, a1, b1); }
;     __device__ __forceinline__ void operator()(const f32x4 (&acc)[2][2][4][2], const Unit& u, int wr, int wc, int fr, int fq) const {
;         const int c0 = u.pn * BM + wc * 32 + 8 * fq;
; #pragma unroll
;         for (int ai = 0; ai < 2; ++ai)
; #pragma unroll
;             for (int mp = 0; mp < 4; mp += 2) {
;                 typename F::Ld ld[2];
; #pragma unroll
;                 for (int m = 0; m < 2; ++m) f.load(ld[m], u.pm * BM + ai * HALF + wr * 64 + (mp + m) * 16 + fr, c0, u.pn, fq);
; #pragma unroll
;                 for (int m = 0; m < 2; ++m) f.apply(ld[m], u.pm * BM + ai * HALF + wr * 64 + (mp + m) * 16 + fr, c0, u.pn, wc, fq, acc[ai][0][mp + m][0], acc[ai][0][mp + m][1], acc[ai][1][mp + m][0], acc[ai][1][mp + m][1]);
;     __device__ __forceinline__ void half(const u32x4& gw, const u32x4& pw, int row, int col, const f32x4& a, const f32x4& b) const {
;         float g[8]; unpack8(gw, g); float p[8]; unpack8(pw, p);
;         f32x4 r0, r1;
; #pragma unroll
;         for (int i = 0; i < 4; ++i) { r0[i] = a[i] * sigmoidf_(g[i]) + p[i]; r1[i] = b[i] * sigmoidf_(g[4 + i]) + p[4 + i]; }
;         *(u32x4*)(merged + (size_t)row * 1024 + col) = pack8(r0, r1);
;     }
;     __device__ __forceinline__ void apply(const Ld& d, int row, int c0, int, int, int, const f32x4& a0, const f32x4& b0, const f32x4& a1, const f32x4& b1) const { half(d.g0, d.p0, row, c0, a0, b0); half(d.g1, d.p1, row, c0 + 128, a1, b1); }
.LBB0_283:
	s_and_b64 vcc, exec, s[0:1]
	s_cbranch_vccz .LBB0_285
	v_lshl_or_b32 v134, s71, 8, v241
	v_ashrrev_i32_e32 v135, 31, v134
	v_readlane_b32 s0, v254, 62
	v_lshlrev_b64 v[164:165], 1, v[134:135]
	v_readlane_b32 s1, v254, 63
	v_mov_b64_e32 v[168:169], s[74:75]
	s_nop 0
	v_lshl_add_u64 v[162:163], s[0:1], 0, v[164:165]
	s_lshl_b32 s0, s63, 8
	v_add_u32_e32 v166, s0, v17
	v_and_b32_e32 v230, 16, v228
	v_lshlrev_b32_e32 v230, 4, v230
	v_and_b32_e32 v231, 32, v228
	v_mul_u32_u24_e32 v231, 0xa0, v231
	v_add_u32_e32 v230, v230, v231
	v_add_u32_e32 v230, 0x800, v230
	v_mov_b32_e32 v231, 0
	v_add_u32_e32 v204, 32, v166
	v_mad_i64_i32 v[204:205], s[50:51], v204, s29, v[168:169]
	v_lshl_add_u64 v[204:205], v[204:205], 0, v[164:165]
	v_lshl_add_u64 v[204:205], v[204:205], 0, v[230:231]
	global_load_dword v220, v[204:205], off
	v_add_u32_e32 v206, 48, v166
	v_mad_i64_i32 v[206:207], s[50:51], v206, s29, v[168:169]
	v_lshl_add_u64 v[206:207], v[206:207], 0, v[164:165]
	v_lshl_add_u64 v[206:207], v[206:207], 0, v[230:231]
	global_load_dword v221, v[206:207], off
	v_add_u32_e32 v208, 0x80, v166
	v_mad_i64_i32 v[208:209], s[50:51], v208, s29, v[168:169]
	v_lshl_add_u64 v[208:209], v[208:209], 0, v[164:165]
	v_lshl_add_u64 v[208:209], v[208:209], 0, v[230:231]
	global_load_dword v222, v[208:209], off
	v_add_u32_e32 v210, 0x90, v166
	v_mad_i64_i32 v[210:211], s[50:51], v210, s29, v[168:169]
	v_lshl_add_u64 v[210:211], v[210:211], 0, v[164:165]
	v_lshl_add_u64 v[210:211], v[210:211], 0, v[230:231]
	global_load_dword v223, v[210:211], off
	v_add_u32_e32 v212, 0xa0, v166
	v_mad_i64_i32 v[212:213], s[50:51], v212, s29, v[168:169]
	v_lshl_add_u64 v[212:213], v[212:213], 0, v[164:165]
	v_lshl_add_u64 v[212:213], v[212:213], 0, v[230:231]
	global_load_dword v224, v[212:213], off
	v_add_u32_e32 v214, 0xb0, v166
	v_mad_i64_i32 v[214:215], s[50:51], v214, s29, v[168:169]
	v_lshl_add_u64 v[214:215], v[214:215], 0, v[164:165]
	v_lshl_add_u64 v[214:215], v[214:215], 0, v[230:231]
	global_load_dword v225, v[214:215], off
	v_mad_i64_i32 v[134:135], s[22:23], v166, s29, v[168:169]
	v_lshl_add_u64 v[134:135], v[134:135], 0, v[164:165]
	v_add_co_u32_e32 v136, vcc, 0x1000, v134
	v_or_b32_e32 v0, 16, v166
	s_nop 0
	v_addc_co_u32_e32 v137, vcc, 0, v135, vcc
	global_load_dwordx4 v[158:161], v[136:137], off offset:3072
	global_load_dwordx4 v[150:153], v[136:137], off offset:3328
	global_load_dwordx4 v[170:173], v[134:135], off offset:2048
	global_load_dwordx4 v[154:157], v[134:135], off offset:2304
	v_mad_i64_i32 v[134:135], s[22:23], v0, s29, v[168:169]
	v_lshl_add_u64 v[134:135], v[134:135], 0, v[164:165]
	v_add_co_u32_e32 v136, vcc, 0x1000, v134
	v_ashrrev_i32_e32 v167, 31, v166
	s_nop 0
	v_addc_co_u32_e32 v137, vcc, 0, v135, vcc
	global_load_dwordx4 v[146:149], v[136:137], off offset:3072
	global_load_dwordx4 v[138:141], v[136:137], off offset:3328
	global_load_dwordx4 v[142:145], v[134:135], off offset:2048
	s_nop 0
	global_load_dwordx4 v[134:137], v[134:135], off offset:2304
	s_waitcnt vmcnt(0)
	v_lshlrev_b32_e32 v0, 16, v158
	v_mul_f32_e32 v0, 0xbfb8aa3b, v0
	v_exp_f32_e32 v0, v0
	v_lshlrev_b32_e32 v175, 16, v160
	v_lshlrev_b32_e32 v177, 16, v170
	v_and_b32_e32 v158, 0xffff0000, v158
	v_add_f32_e32 v0, 1.0, v0
	v_rcp_f32_e32 v0, v0
	v_lshlrev_b32_e32 v179, 16, v172
	v_and_b32_e32 v160, 0xffff0000, v160
	v_and_b32_e32 v170, 0xffff0000, v170
	v_fmac_f32_e32 v177, v130, v0
	v_mul_f32_e32 v0, 0xbfb8aa3b, v175
	v_exp_f32_e32 v0, v0
	v_lshlrev_b32_e32 v174, 16, v159
	v_and_b32_e32 v172, 0xffff0000, v172
	v_lshlrev_b32_e32 v176, 16, v161
	v_add_f32_e32 v0, 1.0, v0
	v_rcp_f32_e32 v0, v0
	v_lshlrev_b32_e32 v178, 16, v171
	v_and_b32_e32 v159, 0xffff0000, v159
	v_lshlrev_b32_e32 v180, 16, v173
	v_fmac_f32_e32 v179, v126, v0
	v_mul_f32_e32 v0, 0xbfb8aa3b, v158
	v_exp_f32_e32 v0, v0
	v_and_b32_e32 v161, 0xffff0000, v161
	v_and_b32_e32 v171, 0xffff0000, v171
	v_and_b32_e32 v173, 0xffff0000, v173
	v_add_f32_e32 v0, 1.0, v0
	v_rcp_f32_e32 v0, v0
	s_nop 0
	v_fmac_f32_e32 v170, v131, v0
	v_mul_f32_e32 v0, 0xbfb8aa3b, v160
	v_exp_f32_e32 v0, v0
	v_cvt_pk_bf16_f32 v158, v177, v170
	s_nop 0
	v_add_f32_e32 v0, 1.0, v0
	v_rcp_f32_e32 v0, v0
	s_nop 0
	v_fmac_f32_e32 v172, v127, v0
	v_mul_f32_e32 v0, 0xbfb8aa3b, v174
	v_exp_f32_e32 v0, v0
	v_add_u32_e32 v174, s0, v236
	v_add_f32_e32 v0, 1.0, v0
	v_rcp_f32_e32 v0, v0
	s_nop 0
	v_fmac_f32_e32 v178, v132, v0
	v_mul_f32_e32 v0, 0xbfb8aa3b, v176
	v_exp_f32_e32 v0, v0
	s_nop 0
	v_add_f32_e32 v0, 1.0, v0
	v_rcp_f32_e32 v0, v0
	s_nop 0
	v_fmac_f32_e32 v180, v128, v0
	v_mul_f32_e32 v0, 0xbfb8aa3b, v159
	v_exp_f32_e32 v0, v0
	s_nop 0
	v_add_f32_e32 v0, 1.0, v0
	v_rcp_f32_e32 v0, v0
	s_nop 0
	v_fmac_f32_e32 v171, v133, v0
	v_mul_f32_e32 v0, 0xbfb8aa3b, v161
	v_exp_f32_e32 v0, v0
	v_cvt_pk_bf16_f32 v159, v178, v171
	v_lshlrev_b64 v[170:171], 11, v[166:167]
	v_cvt_pk_bf16_f32 v160, v179, v172
	v_add_f32_e32 v0, 1.0, v0
	v_rcp_f32_e32 v0, v0
	v_lshl_add_u64 v[170:171], v[162:163], 0, v[170:171]
	v_lshlrev_b32_e32 v172, 16, v156
	v_and_b32_e32 v156, 0xffff0000, v156
	v_fmac_f32_e32 v173, v129, v0
	v_lshlrev_b32_e32 v0, 16, v150
	v_mul_f32_e32 v0, 0xbfb8aa3b, v0
	v_exp_f32_e32 v0, v0
	v_cvt_pk_bf16_f32 v161, v180, v173
	global_store_dwordx4 v[170:171], v[158:161], off
	v_and_b32_e32 v150, 0xffff0000, v150
	v_add_f32_e32 v0, 1.0, v0
	v_rcp_f32_e32 v0, v0
	v_lshlrev_b32_e32 v159, 16, v152
	v_lshlrev_b32_e32 v161, 16, v154
	v_and_b32_e32 v152, 0xffff0000, v152
	v_fmac_f32_e32 v161, v122, v0
	v_mul_f32_e32 v0, 0xbfb8aa3b, v159
	v_exp_f32_e32 v0, v0
	v_and_b32_e32 v154, 0xffff0000, v154
	v_lshlrev_b32_e32 v158, 16, v151
	v_lshlrev_b32_e32 v160, 16, v153
; __device__ __forceinline__ float sigmoidf_(float g) { return __builtin_amdgcn_rcpf(1.f + __expf(-g)); }
; __device__ __forceinline__ u32x4 pack8(const f32x4& a, const f32x4& b) { u32x4 w; w.x = cvt_pk_bf16(a[0], a[1]); w.y = cvt_pk_bf16(a[2], a[3]); w.z = cvt_pk_bf16(b[0], b[1]); w.w = cvt_pk_bf16(b[2], b[3]); return w; }
; __device__ __forceinline__ void unpack8(const u32x4& w, float (&v)[8]) { v[0] = bf_lo(w.x); v[1] = bf_hi(w.x); v[2] = bf_lo(w.y); v[3] = bf_hi(w.y); v[4] = bf_lo(w.z); v[5] = bf_hi(w.z); v[6] = bf_lo(w.w); v[7] = bf_hi(w.w); }
;     __device__ __forceinline__ void apply(const Ld& d, int row, int c0, int, int, int, const f32x4& a0, const f32x4& b0, const f32x4& a1, const f32x4& b1) const { half(d.g0, row, c0, a0, b0); half(d.g1, row, c0 + 128, a1, b1); }
;     __device__ __forceinline__ void half(const u32x4& gw, const u32x4& pw, int row, int col, const f32x4& a, const f32x4& b) const {
;         float g[8]; unpack8(gw, g); float p[8]; unpack8(pw, p);
;         f32x4 r0, r1;
; #pragma unroll
;         for (int i = 0; i < 4; ++i) { r0[i] = a[i] * sigmoidf_(g[i]) + p[i]; r1[i] = b[i] * sigmoidf_(g[4 + i]) + p[4 + i]; }
;         *(u32x4*)(merged + (size_t)row * 1024 + col) = pack8(r0, r1);
;     }
;     __device__ __forceinline__ void apply(const Ld& d, int row, int c0, int, int, int, const f32x4& a0, const f32x4& b0, const f32x4& a1, const f32x4& b1) const { half(d.g0, d.p0, row, c0, a0, b0); half(d.g1, d.p1, row, c0 + 128, a1, b1); }
	v_add_f32_e32 v0, 1.0, v0
	v_rcp_f32_e32 v0, v0
	v_lshlrev_b32_e32 v167, 16, v155
	v_and_b32_e32 v151, 0xffff0000, v151
	v_lshlrev_b32_e32 v173, 16, v157
	v_fmac_f32_e32 v172, v118, v0
	v_mul_f32_e32 v0, 0xbfb8aa3b, v150
	v_exp_f32_e32 v0, v0
	v_and_b32_e32 v153, 0xffff0000, v153
	v_and_b32_e32 v155, 0xffff0000, v155
	v_and_b32_e32 v157, 0xffff0000, v157
	v_add_f32_e32 v0, 1.0, v0
	v_rcp_f32_e32 v0, v0
	s_nop 0
	v_fmac_f32_e32 v154, v123, v0
	v_mul_f32_e32 v0, 0xbfb8aa3b, v152
	v_exp_f32_e32 v0, v0
	v_cvt_pk_bf16_f32 v150, v161, v154
	v_lshlrev_b32_e32 v154, 16, v142
	v_and_b32_e32 v142, 0xffff0000, v142
	v_add_f32_e32 v0, 1.0, v0
	v_rcp_f32_e32 v0, v0
	s_nop 0
	v_fmac_f32_e32 v156, v119, v0
	v_mul_f32_e32 v0, 0xbfb8aa3b, v158
	v_exp_f32_e32 v0, v0
	s_nop 0
	v_add_f32_e32 v0, 1.0, v0
	v_rcp_f32_e32 v0, v0
	s_nop 0
	v_fmac_f32_e32 v167, v124, v0
	v_mul_f32_e32 v0, 0xbfb8aa3b, v160
	v_exp_f32_e32 v0, v0
	s_nop 0
	v_add_f32_e32 v0, 1.0, v0
	v_rcp_f32_e32 v0, v0
	s_nop 0
	v_fmac_f32_e32 v173, v120, v0
	v_mul_f32_e32 v0, 0xbfb8aa3b, v151
	v_exp_f32_e32 v0, v0
	s_nop 0
	v_add_f32_e32 v0, 1.0, v0
	v_rcp_f32_e32 v0, v0
	s_nop 0
	v_fmac_f32_e32 v155, v125, v0
	v_mul_f32_e32 v0, 0xbfb8aa3b, v153
	v_exp_f32_e32 v0, v0
	v_cvt_pk_bf16_f32 v151, v167, v155
	v_cvt_pk_bf16_f32 v152, v172, v156
	v_lshlrev_b32_e32 v156, 16, v144
	v_add_f32_e32 v0, 1.0, v0
	v_rcp_f32_e32 v0, v0
	v_and_b32_e32 v144, 0xffff0000, v144
	v_lshlrev_b32_e32 v155, 16, v143
	v_and_b32_e32 v143, 0xffff0000, v143
	v_fmac_f32_e32 v157, v121, v0
	v_lshlrev_b32_e32 v0, 16, v146
	v_mul_f32_e32 v0, 0xbfb8aa3b, v0
	v_exp_f32_e32 v0, v0
	v_cvt_pk_bf16_f32 v153, v173, v157
	global_store_dwordx4 v[170:171], v[150:153], off offset:256
	v_and_b32_e32 v146, 0xffff0000, v146
	v_add_f32_e32 v0, 1.0, v0
	v_rcp_f32_e32 v0, v0
	v_lshlrev_b32_e32 v152, 16, v148
	v_and_b32_e32 v148, 0xffff0000, v148
	v_lshlrev_b32_e32 v151, 16, v147
	v_fmac_f32_e32 v154, v114, v0
	v_mul_f32_e32 v0, 0xbfb8aa3b, v152
	v_exp_f32_e32 v0, v0
	v_lshlrev_b32_e32 v153, 16, v149
	v_and_b32_e32 v147, 0xffff0000, v147
	v_lshlrev_b32_e32 v157, 16, v145
	v_add_f32_e32 v0, 1.0, v0
	v_rcp_f32_e32 v0, v0
	v_and_b32_e32 v149, 0xffff0000, v149
	v_and_b32_e32 v145, 0xffff0000, v145
	v_add_u32_e32 v150, s0, v235
	v_fmac_f32_e32 v156, v110, v0
	v_mul_f32_e32 v0, 0xbfb8aa3b, v146
	v_exp_f32_e32 v0, v0
	s_nop 0
	v_add_f32_e32 v0, 1.0, v0
	v_rcp_f32_e32 v0, v0
	s_nop 0
	v_fmac_f32_e32 v142, v115, v0
	v_mul_f32_e32 v0, 0xbfb8aa3b, v148
	v_exp_f32_e32 v0, v0
	v_cvt_pk_bf16_f32 v142, v154, v142
	v_lshlrev_b32_e32 v148, 16, v135
	v_and_b32_e32 v135, 0xffff0000, v135
	v_add_f32_e32 v0, 1.0, v0
	v_rcp_f32_e32 v0, v0
	s_nop 0
	v_fmac_f32_e32 v144, v111, v0
	v_mul_f32_e32 v0, 0xbfb8aa3b, v151
	v_exp_f32_e32 v0, v0
	v_ashrrev_i32_e32 v151, 31, v150
	v_add_f32_e32 v0, 1.0, v0
	v_rcp_f32_e32 v0, v0
	s_nop 0
	v_fmac_f32_e32 v155, v116, v0
	v_mul_f32_e32 v0, 0xbfb8aa3b, v153
	v_exp_f32_e32 v0, v0
	s_nop 0
	v_add_f32_e32 v0, 1.0, v0
	v_rcp_f32_e32 v0, v0
	s_nop 0
	v_fmac_f32_e32 v157, v112, v0
	v_mul_f32_e32 v0, 0xbfb8aa3b, v147
	v_exp_f32_e32 v0, v0
	v_lshlrev_b64 v[146:147], 11, v[150:151]
	v_lshl_add_u64 v[146:147], v[162:163], 0, v[146:147]
	v_lshlrev_b32_e32 v150, 16, v137
	v_add_f32_e32 v0, 1.0, v0
	v_rcp_f32_e32 v0, v0
	v_and_b32_e32 v137, 0xffff0000, v137
	v_fmac_f32_e32 v143, v117, v0
	v_mul_f32_e32 v0, 0xbfb8aa3b, v149
	v_exp_f32_e32 v0, v0
	v_cvt_pk_bf16_f32 v143, v155, v143
	v_cvt_pk_bf16_f32 v144, v156, v144
	v_lshlrev_b32_e32 v149, 16, v136
	v_add_f32_e32 v0, 1.0, v0
	v_rcp_f32_e32 v0, v0
	v_and_b32_e32 v136, 0xffff0000, v136
	v_fmac_f32_e32 v145, v113, v0
	v_lshlrev_b32_e32 v0, 16, v138
	v_mul_f32_e32 v0, 0xbfb8aa3b, v0
	v_exp_f32_e32 v0, v0
	v_cvt_pk_bf16_f32 v145, v157, v145
	global_store_dwordx4 v[146:147], v[142:145], off
	v_and_b32_e32 v138, 0xffff0000, v138
	v_add_f32_e32 v0, 1.0, v0
	v_rcp_f32_e32 v0, v0
	v_lshlrev_b32_e32 v143, 16, v140
	v_lshlrev_b32_e32 v145, 16, v134
	v_and_b32_e32 v140, 0xffff0000, v140
	v_fmac_f32_e32 v145, v106, v0
	v_mul_f32_e32 v0, 0xbfb8aa3b, v143
	v_exp_f32_e32 v0, v0
	v_and_b32_e32 v134, 0xffff0000, v134
	v_lshlrev_b32_e32 v142, 16, v139
	v_lshlrev_b32_e32 v144, 16, v141
	v_add_f32_e32 v0, 1.0, v0
	v_rcp_f32_e32 v0, v0
	v_and_b32_e32 v139, 0xffff0000, v139
	v_and_b32_e32 v141, 0xffff0000, v141
	v_fmac_f32_e32 v149, v102, v0
	v_mul_f32_e32 v0, 0xbfb8aa3b, v138
	v_exp_f32_e32 v0, v0
	s_nop 0
	v_add_f32_e32 v0, 1.0, v0
	v_rcp_f32_e32 v0, v0
	s_nop 0
	v_fmac_f32_e32 v134, v107, v0
	v_mul_f32_e32 v0, 0xbfb8aa3b, v140
	v_exp_f32_e32 v0, v0
	v_cvt_pk_bf16_f32 v134, v145, v134
	s_nop 0
	v_add_f32_e32 v0, 1.0, v0
	v_rcp_f32_e32 v0, v0
	s_nop 0
	v_fmac_f32_e32 v136, v103, v0
	v_mul_f32_e32 v0, 0xbfb8aa3b, v142
	v_exp_f32_e32 v0, v0
	s_nop 0
	v_add_f32_e32 v0, 1.0, v0
	v_rcp_f32_e32 v0, v0
	s_nop 0
	v_fmac_f32_e32 v148, v108, v0
	v_mul_f32_e32 v0, 0xbfb8aa3b, v144
	v_exp_f32_e32 v0, v0
	s_nop 0
	v_add_f32_e32 v0, 1.0, v0
	v_rcp_f32_e32 v0, v0
	s_nop 0
	v_fmac_f32_e32 v150, v104, v0
	v_mul_f32_e32 v0, 0xbfb8aa3b, v139
	v_exp_f32_e32 v0, v0
	s_nop 0
	v_add_f32_e32 v0, 1.0, v0
	v_rcp_f32_e32 v0, v0
	s_nop 0
	v_fmac_f32_e32 v135, v109, v0
	v_mul_f32_e32 v0, 0xbfb8aa3b, v141
	v_exp_f32_e32 v0, v0
	v_cvt_pk_bf16_f32 v135, v148, v135
	v_cvt_pk_bf16_f32 v136, v149, v136
	s_nop 0
	v_add_f32_e32 v0, 1.0, v0
	v_rcp_f32_e32 v0, v0
	s_nop 0
	v_fmac_f32_e32 v137, v105, v0
	v_or_b32_e32 v0, 32, v166
	v_cvt_pk_bf16_f32 v137, v150, v137
	global_store_dwordx4 v[146:147], v[134:137], off offset:256
	s_nop 1
	v_mad_i64_i32 v[134:135], s[22:23], v0, s29, v[168:169]
	v_lshl_add_u64 v[134:135], v[134:135], 0, v[164:165]
	v_add_co_u32_e32 v136, vcc, s98, v134
	v_or_b32_e32 v0, 48, v166
	s_nop 0
	v_addc_co_u32_e32 v137, vcc, 0, v135, vcc
	global_load_dwordx4 v[154:157], v[136:137], off offset:3072
	global_load_dwordx4 v[150:153], v[136:137], off offset:3328
	global_load_dwordx4 v[158:161], v[134:135], off offset:2048
	global_load_dwordx4 v[170:173], v[134:135], off offset:2304
	v_mad_i64_i32 v[134:135], s[22:23], v0, s29, v[168:169]
	v_lshl_add_u64 v[134:135], v[134:135], 0, v[164:165]
	v_add_co_u32_e32 v136, vcc, s98, v134
	s_waitcnt vmcnt(0)
; __device__ __forceinline__ float sigmoidf_(float g) { return __builtin_amdgcn_rcpf(1.f + __expf(-g)); }
; __device__ __forceinline__ u32x4 pack8(const f32x4& a, const f32x4& b) { u32x4 w; w.x = cvt_pk_bf16(a[0], a[1]); w.y = cvt_pk_bf16(a[2], a[3]); w.z = cvt_pk_bf16(b[0], b[1]); w.w = cvt_pk_bf16(b[2], b[3]); return w; }
; __device__ __forceinline__ void unpack8(const u32x4& w, float (&v)[8]) { v[0] = bf_lo(w.x); v[1] = bf_hi(w.x); v[2] = bf_lo(w.y); v[3] = bf_hi(w.y); v[4] = bf_lo(w.z); v[5] = bf_hi(w.z); v[6] = bf_lo(w.w); v[7] = bf_hi(w.w); }
;     __device__ __forceinline__ void apply(const Ld& d, int row, int c0, int, int, int, const f32x4& a0, const f32x4& b0, const f32x4& a1, const f32x4& b1) const { half(d.g0, row, c0, a0, b0); half(d.g1, row, c0 + 128, a1, b1); }
;     __device__ __forceinline__ void half(const u32x4& gw, const u32x4& pw, int row, int col, const f32x4& a, const f32x4& b) const {
;         float g[8]; unpack8(gw, g); float p[8]; unpack8(pw, p);
;         f32x4 r0, r1;
; #pragma unroll
;         for (int i = 0; i < 4; ++i) { r0[i] = a[i] * sigmoidf_(g[i]) + p[i]; r1[i] = b[i] * sigmoidf_(g[4 + i]) + p[4 + i]; }
;         *(u32x4*)(merged + (size_t)row * 1024 + col) = pack8(r0, r1);
;     }
;     __device__ __forceinline__ void apply(const Ld& d, int row, int c0, int, int, int, const f32x4& a0, const f32x4& b0, const f32x4& a1, const f32x4& b1) const { half(d.g0, d.p0, row, c0, a0, b0); half(d.g1, d.p1, row, c0 + 128, a1, b1); }
	v_lshlrev_b32_e32 v0, 16, v154
	v_mul_f32_e32 v0, 0xbfb8aa3b, v0
	v_exp_f32_e32 v0, v0
	v_lshlrev_b32_e32 v175, 16, v156
	v_lshlrev_b32_e32 v177, 16, v158
	v_and_b32_e32 v154, 0xffff0000, v154
	v_add_f32_e32 v0, 1.0, v0
	v_rcp_f32_e32 v0, v0
	v_lshlrev_b32_e32 v179, 16, v160
	v_and_b32_e32 v156, 0xffff0000, v156
	v_and_b32_e32 v158, 0xffff0000, v158
	v_fmac_f32_e32 v177, v98, v0
	v_mul_f32_e32 v0, 0xbfb8aa3b, v175
	v_exp_f32_e32 v0, v0
	v_lshlrev_b32_e32 v167, 16, v155
	v_and_b32_e32 v160, 0xffff0000, v160
	v_lshlrev_b32_e32 v176, 16, v157
	v_add_f32_e32 v0, 1.0, v0
	v_rcp_f32_e32 v0, v0
	v_lshlrev_b32_e32 v178, 16, v159
	v_and_b32_e32 v155, 0xffff0000, v155
	v_lshlrev_b32_e32 v180, 16, v161
	v_fmac_f32_e32 v179, v94, v0
	v_mul_f32_e32 v0, 0xbfb8aa3b, v154
	v_exp_f32_e32 v0, v0
	v_and_b32_e32 v157, 0xffff0000, v157
	v_and_b32_e32 v159, 0xffff0000, v159
	v_and_b32_e32 v161, 0xffff0000, v161
	v_add_f32_e32 v0, 1.0, v0
	v_rcp_f32_e32 v0, v0
	v_addc_co_u32_e32 v137, vcc, 0, v135, vcc
	global_load_dwordx4 v[146:149], v[136:137], off offset:3072
	global_load_dwordx4 v[138:141], v[136:137], off offset:3328
	global_load_dwordx4 v[142:145], v[134:135], off offset:2048
	s_nop 0
	global_load_dwordx4 v[134:137], v[134:135], off offset:2304
	v_fmac_f32_e32 v158, v99, v0
	v_mul_f32_e32 v0, 0xbfb8aa3b, v156
	v_exp_f32_e32 v0, v0
	v_ashrrev_i32_e32 v175, 31, v174
	v_cvt_pk_bf16_f32 v154, v177, v158
	v_add_f32_e32 v0, 1.0, v0
	v_rcp_f32_e32 v0, v0
	s_nop 0
	v_fmac_f32_e32 v160, v95, v0
	v_mul_f32_e32 v0, 0xbfb8aa3b, v167
	v_exp_f32_e32 v0, v0
	v_and_b32_e32 v167, 0xffff0000, v171
	v_add_f32_e32 v0, 1.0, v0
	v_rcp_f32_e32 v0, v0
	s_nop 0
	v_fmac_f32_e32 v178, v100, v0
	v_mul_f32_e32 v0, 0xbfb8aa3b, v176
	v_exp_f32_e32 v0, v0
	s_nop 0
	v_add_f32_e32 v0, 1.0, v0
	v_rcp_f32_e32 v0, v0
	s_nop 0
	v_fmac_f32_e32 v180, v96, v0
	v_mul_f32_e32 v0, 0xbfb8aa3b, v155
	v_exp_f32_e32 v0, v0
	s_nop 0
	v_add_f32_e32 v0, 1.0, v0
	v_rcp_f32_e32 v0, v0
	s_nop 0
	v_fmac_f32_e32 v159, v101, v0
	v_mul_f32_e32 v0, 0xbfb8aa3b, v157
	v_exp_f32_e32 v0, v0
	v_cvt_pk_bf16_f32 v155, v178, v159
	v_lshlrev_b64 v[158:159], 11, v[174:175]
	v_cvt_pk_bf16_f32 v156, v179, v160
	v_add_f32_e32 v0, 1.0, v0
	v_rcp_f32_e32 v0, v0
	v_lshl_add_u64 v[158:159], v[162:163], 0, v[158:159]
	v_and_b32_e32 v160, 0xffff0000, v170
	v_fmac_f32_e32 v161, v97, v0
	v_lshlrev_b32_e32 v0, 16, v150
	v_mul_f32_e32 v0, 0xbfb8aa3b, v0
	v_exp_f32_e32 v0, v0
	v_cvt_pk_bf16_f32 v157, v180, v161
	global_store_dwordx4 v[158:159], v[154:157], off
	v_and_b32_e32 v150, 0xffff0000, v150
	v_add_f32_e32 v0, 1.0, v0
	v_rcp_f32_e32 v0, v0
	v_lshlrev_b32_e32 v155, 16, v152
	v_lshlrev_b32_e32 v157, 16, v170
	v_lshlrev_b32_e32 v170, 16, v172
	v_fmac_f32_e32 v157, v90, v0
	v_mul_f32_e32 v0, 0xbfb8aa3b, v155
	v_exp_f32_e32 v0, v0
	v_and_b32_e32 v152, 0xffff0000, v152
	v_lshlrev_b32_e32 v154, 16, v151
	v_lshlrev_b32_e32 v161, 16, v171
	v_add_f32_e32 v0, 1.0, v0
	v_rcp_f32_e32 v0, v0
	v_and_b32_e32 v171, 0xffff0000, v172
	v_lshlrev_b32_e32 v156, 16, v153
	v_and_b32_e32 v151, 0xffff0000, v151
	v_fmac_f32_e32 v170, v86, v0
	v_mul_f32_e32 v0, 0xbfb8aa3b, v150
	v_exp_f32_e32 v0, v0
	v_lshlrev_b32_e32 v172, 16, v173
	v_and_b32_e32 v153, 0xffff0000, v153
	v_and_b32_e32 v173, 0xffff0000, v173
	v_add_f32_e32 v0, 1.0, v0
	v_rcp_f32_e32 v0, v0
	s_waitcnt vmcnt(1)
	v_lshlrev_b32_e32 v155, 16, v143
	v_and_b32_e32 v143, 0xffff0000, v143
	v_fmac_f32_e32 v160, v91, v0
	v_mul_f32_e32 v0, 0xbfb8aa3b, v152
	v_exp_f32_e32 v0, v0
	v_cvt_pk_bf16_f32 v150, v157, v160
	v_lshlrev_b32_e32 v157, 16, v145
	v_and_b32_e32 v145, 0xffff0000, v145
	v_add_f32_e32 v0, 1.0, v0
	v_rcp_f32_e32 v0, v0
	s_nop 0
	v_fmac_f32_e32 v171, v87, v0
	v_mul_f32_e32 v0, 0xbfb8aa3b, v154
	v_exp_f32_e32 v0, v0
	v_lshlrev_b32_e32 v154, 16, v142
	v_and_b32_e32 v142, 0xffff0000, v142
	v_add_f32_e32 v0, 1.0, v0
	v_rcp_f32_e32 v0, v0
	s_nop 0
	v_fmac_f32_e32 v161, v92, v0
	v_mul_f32_e32 v0, 0xbfb8aa3b, v156
	v_exp_f32_e32 v0, v0
	v_lshlrev_b32_e32 v156, 16, v144
	v_and_b32_e32 v144, 0xffff0000, v144
	v_add_f32_e32 v0, 1.0, v0
	v_rcp_f32_e32 v0, v0
	s_nop 0
	v_fmac_f32_e32 v172, v88, v0
	v_mul_f32_e32 v0, 0xbfb8aa3b, v151
	v_exp_f32_e32 v0, v0
	s_nop 0
	v_add_f32_e32 v0, 1.0, v0
	v_rcp_f32_e32 v0, v0
	s_nop 0
	v_fmac_f32_e32 v167, v93, v0
	v_mul_f32_e32 v0, 0xbfb8aa3b, v153
	v_exp_f32_e32 v0, v0
	v_cvt_pk_bf16_f32 v151, v161, v167
	v_cvt_pk_bf16_f32 v152, v170, v171
	s_nop 0
	v_add_f32_e32 v0, 1.0, v0
	v_rcp_f32_e32 v0, v0
	s_nop 0
	v_fmac_f32_e32 v173, v89, v0
	v_lshlrev_b32_e32 v0, 16, v146
	v_mul_f32_e32 v0, 0xbfb8aa3b, v0
	v_exp_f32_e32 v0, v0
	v_cvt_pk_bf16_f32 v153, v172, v173
	global_store_dwordx4 v[158:159], v[150:153], off offset:256
	v_and_b32_e32 v146, 0xffff0000, v146
	v_add_f32_e32 v0, 1.0, v0
	v_rcp_f32_e32 v0, v0
	v_lshlrev_b32_e32 v152, 16, v148
	v_and_b32_e32 v148, 0xffff0000, v148
	v_lshlrev_b32_e32 v151, 16, v147
	v_fmac_f32_e32 v154, v82, v0
	v_mul_f32_e32 v0, 0xbfb8aa3b, v152
	v_exp_f32_e32 v0, v0
	v_lshlrev_b32_e32 v153, 16, v149
	v_and_b32_e32 v147, 0xffff0000, v147
	v_and_b32_e32 v149, 0xffff0000, v149
	v_add_f32_e32 v0, 1.0, v0
	v_rcp_f32_e32 v0, v0
	v_add_u32_e32 v150, s0, v237
	v_fmac_f32_e32 v156, v78, v0
	v_mul_f32_e32 v0, 0xbfb8aa3b, v146
	v_exp_f32_e32 v0, v0
	s_nop 0
	v_add_f32_e32 v0, 1.0, v0
	v_rcp_f32_e32 v0, v0
	s_nop 0
	v_fmac_f32_e32 v142, v83, v0
	v_mul_f32_e32 v0, 0xbfb8aa3b, v148
	v_exp_f32_e32 v0, v0
	v_cvt_pk_bf16_f32 v142, v154, v142
	v_lshlrev_b32_e32 v148, 16, v135
	v_and_b32_e32 v135, 0xffff0000, v135
	v_add_f32_e32 v0, 1.0, v0
	v_rcp_f32_e32 v0, v0
	v_add_u32_e32 v154, 0x80, v166
	v_fmac_f32_e32 v144, v79, v0
	v_mul_f32_e32 v0, 0xbfb8aa3b, v151
; __device__ __forceinline__ float sigmoidf_(float g) { return __builtin_amdgcn_rcpf(1.f + __expf(-g)); }
; __device__ __forceinline__ u32x4 pack8(const f32x4& a, const f32x4& b) { u32x4 w; w.x = cvt_pk_bf16(a[0], a[1]); w.y = cvt_pk_bf16(a[2], a[3]); w.z = cvt_pk_bf16(b[0], b[1]); w.w = cvt_pk_bf16(b[2], b[3]); return w; }
; __device__ __forceinline__ void unpack8(const u32x4& w, float (&v)[8]) { v[0] = bf_lo(w.x); v[1] = bf_hi(w.x); v[2] = bf_lo(w.y); v[3] = bf_hi(w.y); v[4] = bf_lo(w.z); v[5] = bf_hi(w.z); v[6] = bf_lo(w.w); v[7] = bf_hi(w.w); }
;     __device__ __forceinline__ void apply(const Ld& d, int row, int c0, int, int, int, const f32x4& a0, const f32x4& b0, const f32x4& a1, const f32x4& b1) const { half(d.g0, row, c0, a0, b0); half(d.g1, row, c0 + 128, a1, b1); }
;     __device__ __forceinline__ void half(const u32x4& gw, const u32x4& pw, int row, int col, const f32x4& a, const f32x4& b) const {
;         float g[8]; unpack8(gw, g); float p[8]; unpack8(pw, p);
;         f32x4 r0, r1;
; #pragma unroll
;         for (int i = 0; i < 4; ++i) { r0[i] = a[i] * sigmoidf_(g[i]) + p[i]; r1[i] = b[i] * sigmoidf_(g[4 + i]) + p[4 + i]; }
;         *(u32x4*)(merged + (size_t)row * 1024 + col) = pack8(r0, r1);
;     }
;     __device__ __forceinline__ void apply(const Ld& d, int row, int c0, int, int, int, const f32x4& a0, const f32x4& b0, const f32x4& a1, const f32x4& b1) const { half(d.g0, d.p0, row, c0, a0, b0); half(d.g1, d.p1, row, c0 + 128, a1, b1); }
	v_exp_f32_e32 v0, v0
	v_ashrrev_i32_e32 v151, 31, v150
	v_add_f32_e32 v0, 1.0, v0
	v_rcp_f32_e32 v0, v0
	s_nop 0
	v_fmac_f32_e32 v155, v84, v0
	v_mul_f32_e32 v0, 0xbfb8aa3b, v153
	v_exp_f32_e32 v0, v0
	s_nop 0
	v_add_f32_e32 v0, 1.0, v0
	v_rcp_f32_e32 v0, v0
	s_nop 0
	v_fmac_f32_e32 v157, v80, v0
	v_mul_f32_e32 v0, 0xbfb8aa3b, v147
	v_exp_f32_e32 v0, v0
	v_lshlrev_b64 v[146:147], 11, v[150:151]
	v_lshl_add_u64 v[146:147], v[162:163], 0, v[146:147]
	v_lshlrev_b32_e32 v150, 16, v137
	v_add_f32_e32 v0, 1.0, v0
	v_rcp_f32_e32 v0, v0
	v_and_b32_e32 v137, 0xffff0000, v137
	v_fmac_f32_e32 v143, v85, v0
	v_mul_f32_e32 v0, 0xbfb8aa3b, v149
	v_exp_f32_e32 v0, v0
	v_cvt_pk_bf16_f32 v143, v155, v143
	v_cvt_pk_bf16_f32 v144, v156, v144
	v_lshlrev_b32_e32 v149, 16, v136
	v_add_f32_e32 v0, 1.0, v0
	v_rcp_f32_e32 v0, v0
	v_and_b32_e32 v136, 0xffff0000, v136
	v_ashrrev_i32_e32 v155, 31, v154
	v_fmac_f32_e32 v145, v81, v0
	v_lshlrev_b32_e32 v0, 16, v138
	v_mul_f32_e32 v0, 0xbfb8aa3b, v0
	v_exp_f32_e32 v0, v0
	v_cvt_pk_bf16_f32 v145, v157, v145
	global_store_dwordx4 v[146:147], v[142:145], off
	v_and_b32_e32 v138, 0xffff0000, v138
	v_add_f32_e32 v0, 1.0, v0
	v_rcp_f32_e32 v0, v0
	v_lshlrev_b32_e32 v143, 16, v140
	v_lshlrev_b32_e32 v145, 16, v134
	v_and_b32_e32 v140, 0xffff0000, v140
	v_fmac_f32_e32 v145, v74, v0
	v_mul_f32_e32 v0, 0xbfb8aa3b, v143
	v_exp_f32_e32 v0, v0
	v_and_b32_e32 v134, 0xffff0000, v134
	v_lshlrev_b32_e32 v142, 16, v139
	v_lshlrev_b32_e32 v144, 16, v141
	v_add_f32_e32 v0, 1.0, v0
	v_rcp_f32_e32 v0, v0
	v_and_b32_e32 v139, 0xffff0000, v139
	v_and_b32_e32 v141, 0xffff0000, v141
	v_fmac_f32_e32 v149, v70, v0
	v_mul_f32_e32 v0, 0xbfb8aa3b, v138
	v_exp_f32_e32 v0, v0
	s_nop 0
	v_add_f32_e32 v0, 1.0, v0
	v_rcp_f32_e32 v0, v0
	s_nop 0
	v_fmac_f32_e32 v134, v75, v0
	v_mul_f32_e32 v0, 0xbfb8aa3b, v140
	v_exp_f32_e32 v0, v0
	v_cvt_pk_bf16_f32 v134, v145, v134
	s_nop 0
	v_add_f32_e32 v0, 1.0, v0
	v_rcp_f32_e32 v0, v0
	s_nop 0
	v_fmac_f32_e32 v136, v71, v0
	v_mul_f32_e32 v0, 0xbfb8aa3b, v142
	v_exp_f32_e32 v0, v0
	s_nop 0
	v_add_f32_e32 v0, 1.0, v0
	v_rcp_f32_e32 v0, v0
	s_nop 0
	v_fmac_f32_e32 v148, v76, v0
	v_mul_f32_e32 v0, 0xbfb8aa3b, v144
	v_exp_f32_e32 v0, v0
	s_nop 0
	v_add_f32_e32 v0, 1.0, v0
	v_rcp_f32_e32 v0, v0
	s_nop 0
	v_fmac_f32_e32 v150, v72, v0
	v_mul_f32_e32 v0, 0xbfb8aa3b, v139
	v_exp_f32_e32 v0, v0
	s_nop 0
	v_add_f32_e32 v0, 1.0, v0
	v_rcp_f32_e32 v0, v0
	s_nop 0
	v_fmac_f32_e32 v135, v77, v0
	v_mul_f32_e32 v0, 0xbfb8aa3b, v141
	v_exp_f32_e32 v0, v0
	v_cvt_pk_bf16_f32 v135, v148, v135
	v_cvt_pk_bf16_f32 v136, v149, v136
	s_nop 0
	v_add_f32_e32 v0, 1.0, v0
	v_rcp_f32_e32 v0, v0
	s_nop 0
	v_fmac_f32_e32 v137, v73, v0
	v_cvt_pk_bf16_f32 v137, v150, v137
	global_store_dwordx4 v[146:147], v[134:137], off offset:256
	v_add_u32_e32 v0, 0x90, v166
	s_nop 0
	v_mad_i64_i32 v[134:135], s[22:23], v154, s29, v[168:169]
	v_lshl_add_u64 v[134:135], v[134:135], 0, v[164:165]
	v_add_co_u32_e32 v136, vcc, s98, v134
	v_lshlrev_b64 v[154:155], 11, v[154:155]
	s_nop 0
	v_addc_co_u32_e32 v137, vcc, 0, v135, vcc
	global_load_dwordx4 v[156:159], v[136:137], off offset:3072
	global_load_dwordx4 v[150:153], v[136:137], off offset:3328
	global_load_dwordx4 v[170:173], v[134:135], off offset:2048
	global_load_dwordx4 v[174:177], v[134:135], off offset:2304
	v_mad_i64_i32 v[134:135], s[22:23], v0, s29, v[168:169]
	v_lshl_add_u64 v[134:135], v[134:135], 0, v[164:165]
	v_add_co_u32_e32 v136, vcc, s98, v134
	v_lshl_add_u64 v[154:155], v[162:163], 0, v[154:155]
	s_nop 0
	v_addc_co_u32_e32 v137, vcc, 0, v135, vcc
	global_load_dwordx4 v[146:149], v[136:137], off offset:3072
	global_load_dwordx4 v[138:141], v[136:137], off offset:3328
	global_load_dwordx4 v[142:145], v[134:135], off offset:2048
	s_nop 0
	global_load_dwordx4 v[134:137], v[134:135], off offset:2304
	s_waitcnt vmcnt(0)
	v_lshlrev_b32_e32 v0, 16, v156
	v_mul_f32_e32 v0, 0xbfb8aa3b, v0
	v_exp_f32_e32 v0, v0
	v_lshlrev_b32_e32 v161, 16, v158
	v_lshlrev_b32_e32 v178, 16, v170
	v_and_b32_e32 v156, 0xffff0000, v156
	v_add_f32_e32 v0, 1.0, v0
	v_rcp_f32_e32 v0, v0
	v_lshlrev_b32_e32 v180, 16, v172
	v_and_b32_e32 v158, 0xffff0000, v158
	v_and_b32_e32 v170, 0xffff0000, v170
	v_fmac_f32_e32 v178, v66, v0
	v_mul_f32_e32 v0, 0xbfb8aa3b, v161
	v_exp_f32_e32 v0, v0
	v_lshlrev_b32_e32 v160, 16, v157
	v_and_b32_e32 v172, 0xffff0000, v172
	v_lshlrev_b32_e32 v167, 16, v159
	v_add_f32_e32 v0, 1.0, v0
	v_rcp_f32_e32 v0, v0
	v_lshlrev_b32_e32 v179, 16, v171
	v_and_b32_e32 v157, 0xffff0000, v157
	v_lshlrev_b32_e32 v181, 16, v173
	v_fmac_f32_e32 v180, v62, v0
	v_mul_f32_e32 v0, 0xbfb8aa3b, v156
	v_exp_f32_e32 v0, v0
	v_and_b32_e32 v159, 0xffff0000, v159
	v_and_b32_e32 v171, 0xffff0000, v171
	v_and_b32_e32 v173, 0xffff0000, v173
	v_add_f32_e32 v0, 1.0, v0
	v_rcp_f32_e32 v0, v0
	v_lshlrev_b32_e32 v161, 16, v175
	v_fmac_f32_e32 v170, v67, v0
	v_mul_f32_e32 v0, 0xbfb8aa3b, v158
	v_exp_f32_e32 v0, v0
	v_cvt_pk_bf16_f32 v156, v178, v170
	v_lshlrev_b32_e32 v170, 16, v176
	v_add_f32_e32 v0, 1.0, v0
	v_rcp_f32_e32 v0, v0
	s_nop 0
	v_fmac_f32_e32 v172, v63, v0
	v_mul_f32_e32 v0, 0xbfb8aa3b, v160
	v_exp_f32_e32 v0, v0
	v_and_b32_e32 v160, 0xffff0000, v174
	v_add_f32_e32 v0, 1.0, v0
	v_rcp_f32_e32 v0, v0
	s_nop 0
	v_fmac_f32_e32 v179, v68, v0
	v_mul_f32_e32 v0, 0xbfb8aa3b, v167
	v_exp_f32_e32 v0, v0
	v_and_b32_e32 v167, 0xffff0000, v175
	v_add_f32_e32 v0, 1.0, v0
	v_rcp_f32_e32 v0, v0
	s_nop 0
	v_fmac_f32_e32 v181, v64, v0
	v_mul_f32_e32 v0, 0xbfb8aa3b, v157
	v_exp_f32_e32 v0, v0
	s_nop 0
	v_add_f32_e32 v0, 1.0, v0
	v_rcp_f32_e32 v0, v0
	s_nop 0
	v_fmac_f32_e32 v171, v69, v0
	v_mul_f32_e32 v0, 0xbfb8aa3b, v159
	v_exp_f32_e32 v0, v0
; __device__ __forceinline__ float sigmoidf_(float g) { return __builtin_amdgcn_rcpf(1.f + __expf(-g)); }
; __device__ __forceinline__ u32x4 pack8(const f32x4& a, const f32x4& b) { u32x4 w; w.x = cvt_pk_bf16(a[0], a[1]); w.y = cvt_pk_bf16(a[2], a[3]); w.z = cvt_pk_bf16(b[0], b[1]); w.w = cvt_pk_bf16(b[2], b[3]); return w; }
; __device__ __forceinline__ void unpack8(const u32x4& w, float (&v)[8]) { v[0] = bf_lo(w.x); v[1] = bf_hi(w.x); v[2] = bf_lo(w.y); v[3] = bf_hi(w.y); v[4] = bf_lo(w.z); v[5] = bf_hi(w.z); v[6] = bf_lo(w.w); v[7] = bf_hi(w.w); }
;     __device__ __forceinline__ void apply(const Ld& d, int row, int c0, int, int, int, const f32x4& a0, const f32x4& b0, const f32x4& a1, const f32x4& b1) const { half(d.g0, row, c0, a0, b0); half(d.g1, row, c0 + 128, a1, b1); }
;     __device__ __forceinline__ void half(const u32x4& gw, const u32x4& pw, int row, int col, const f32x4& a, const f32x4& b) const {
;         float g[8]; unpack8(gw, g); float p[8]; unpack8(pw, p);
;         f32x4 r0, r1;
; #pragma unroll
;         for (int i = 0; i < 4; ++i) { r0[i] = a[i] * sigmoidf_(g[i]) + p[i]; r1[i] = b[i] * sigmoidf_(g[4 + i]) + p[4 + i]; }
;         *(u32x4*)(merged + (size_t)row * 1024 + col) = pack8(r0, r1);
;     }
;     __device__ __forceinline__ void apply(const Ld& d, int row, int c0, int, int, int, const f32x4& a0, const f32x4& b0, const f32x4& a1, const f32x4& b1) const { half(d.g0, d.p0, row, c0, a0, b0); half(d.g1, d.p1, row, c0 + 128, a1, b1); }
	v_cvt_pk_bf16_f32 v157, v179, v171
	v_cvt_pk_bf16_f32 v158, v180, v172
	v_and_b32_e32 v171, 0xffff0000, v176
	v_add_f32_e32 v0, 1.0, v0
	v_rcp_f32_e32 v0, v0
	v_lshlrev_b32_e32 v172, 16, v177
	v_fmac_f32_e32 v173, v65, v0
	v_lshlrev_b32_e32 v0, 16, v150
	v_mul_f32_e32 v0, 0xbfb8aa3b, v0
	v_exp_f32_e32 v0, v0
	v_cvt_pk_bf16_f32 v159, v181, v173
	global_store_dwordx4 v[154:155], v[156:159], off
	v_and_b32_e32 v150, 0xffff0000, v150
	v_add_f32_e32 v0, 1.0, v0
	v_rcp_f32_e32 v0, v0
	v_lshlrev_b32_e32 v157, 16, v152
	v_lshlrev_b32_e32 v159, 16, v174
	v_and_b32_e32 v152, 0xffff0000, v152
	v_fmac_f32_e32 v159, v58, v0
	v_mul_f32_e32 v0, 0xbfb8aa3b, v157
	v_exp_f32_e32 v0, v0
	v_lshlrev_b32_e32 v156, 16, v151
	v_lshlrev_b32_e32 v158, 16, v153
	v_and_b32_e32 v151, 0xffff0000, v151
	v_add_f32_e32 v0, 1.0, v0
	v_rcp_f32_e32 v0, v0
	v_and_b32_e32 v153, 0xffff0000, v153
	v_and_b32_e32 v173, 0xffff0000, v177
	v_lshlrev_b32_e32 v157, 16, v145
	v_fmac_f32_e32 v170, v54, v0
	v_mul_f32_e32 v0, 0xbfb8aa3b, v150
	v_exp_f32_e32 v0, v0
	v_and_b32_e32 v145, 0xffff0000, v145
	v_add_f32_e32 v0, 1.0, v0
	v_rcp_f32_e32 v0, v0
	s_nop 0
	v_fmac_f32_e32 v160, v59, v0
	v_mul_f32_e32 v0, 0xbfb8aa3b, v152
	v_exp_f32_e32 v0, v0
	v_cvt_pk_bf16_f32 v150, v159, v160
	s_nop 0
	v_add_f32_e32 v0, 1.0, v0
	v_rcp_f32_e32 v0, v0
	s_nop 0
	v_fmac_f32_e32 v171, v55, v0
	v_mul_f32_e32 v0, 0xbfb8aa3b, v156
	v_exp_f32_e32 v0, v0
	v_lshlrev_b32_e32 v156, 16, v144
	v_and_b32_e32 v144, 0xffff0000, v144
	v_add_f32_e32 v0, 1.0, v0
	v_rcp_f32_e32 v0, v0
	s_nop 0
	v_fmac_f32_e32 v161, v60, v0
	v_mul_f32_e32 v0, 0xbfb8aa3b, v158
	v_exp_f32_e32 v0, v0
	s_nop 0
	v_add_f32_e32 v0, 1.0, v0
	v_rcp_f32_e32 v0, v0
	s_nop 0
	v_fmac_f32_e32 v172, v56, v0
	v_mul_f32_e32 v0, 0xbfb8aa3b, v151
	v_exp_f32_e32 v0, v0
	s_nop 0
	v_add_f32_e32 v0, 1.0, v0
	v_rcp_f32_e32 v0, v0
	s_nop 0
	v_fmac_f32_e32 v167, v61, v0
	v_mul_f32_e32 v0, 0xbfb8aa3b, v153
	v_exp_f32_e32 v0, v0
	v_cvt_pk_bf16_f32 v151, v161, v167
	v_cvt_pk_bf16_f32 v152, v170, v171
	s_nop 0
	v_add_f32_e32 v0, 1.0, v0
	v_rcp_f32_e32 v0, v0
	s_nop 0
	v_fmac_f32_e32 v173, v57, v0
	v_lshlrev_b32_e32 v0, 16, v146
	v_mul_f32_e32 v0, 0xbfb8aa3b, v0
	v_exp_f32_e32 v0, v0
	v_cvt_pk_bf16_f32 v153, v172, v173
	global_store_dwordx4 v[154:155], v[150:153], off offset:256
	v_lshlrev_b32_e32 v154, 16, v142
	v_add_f32_e32 v0, 1.0, v0
	v_rcp_f32_e32 v0, v0
	v_lshlrev_b32_e32 v152, 16, v148
	v_and_b32_e32 v146, 0xffff0000, v146
	v_and_b32_e32 v148, 0xffff0000, v148
	v_fmac_f32_e32 v154, v50, v0
	v_mul_f32_e32 v0, 0xbfb8aa3b, v152
	v_exp_f32_e32 v0, v0
	v_and_b32_e32 v142, 0xffff0000, v142
	v_lshlrev_b32_e32 v151, 16, v147
	v_lshlrev_b32_e32 v153, 16, v149
	v_add_f32_e32 v0, 1.0, v0
	v_rcp_f32_e32 v0, v0
	v_lshlrev_b32_e32 v155, 16, v143
	v_and_b32_e32 v147, 0xffff0000, v147
	v_and_b32_e32 v149, 0xffff0000, v149
	v_fmac_f32_e32 v156, v46, v0
	v_mul_f32_e32 v0, 0xbfb8aa3b, v146
	v_exp_f32_e32 v0, v0
	v_and_b32_e32 v143, 0xffff0000, v143
	v_add_u32_e32 v150, s0, v238
	v_add_f32_e32 v0, 1.0, v0
	v_rcp_f32_e32 v0, v0
	s_nop 0
	v_fmac_f32_e32 v142, v51, v0
	v_mul_f32_e32 v0, 0xbfb8aa3b, v148
	v_exp_f32_e32 v0, v0
	v_cvt_pk_bf16_f32 v142, v154, v142
	v_lshlrev_b32_e32 v148, 16, v135
	v_and_b32_e32 v135, 0xffff0000, v135
	v_add_f32_e32 v0, 1.0, v0
	v_rcp_f32_e32 v0, v0
	s_nop 0
	v_fmac_f32_e32 v144, v47, v0
	v_mul_f32_e32 v0, 0xbfb8aa3b, v151
	v_exp_f32_e32 v0, v0
	v_ashrrev_i32_e32 v151, 31, v150
	v_add_f32_e32 v0, 1.0, v0
	v_rcp_f32_e32 v0, v0
	s_nop 0
	v_fmac_f32_e32 v155, v52, v0
	v_mul_f32_e32 v0, 0xbfb8aa3b, v153
	v_exp_f32_e32 v0, v0
	s_nop 0
	v_add_f32_e32 v0, 1.0, v0
	v_rcp_f32_e32 v0, v0
	s_nop 0
	v_fmac_f32_e32 v157, v48, v0
	v_mul_f32_e32 v0, 0xbfb8aa3b, v147
	v_exp_f32_e32 v0, v0
	v_lshlrev_b64 v[146:147], 11, v[150:151]
	v_lshl_add_u64 v[146:147], v[162:163], 0, v[146:147]
	v_lshlrev_b32_e32 v150, 16, v137
	v_add_f32_e32 v0, 1.0, v0
	v_rcp_f32_e32 v0, v0
	v_and_b32_e32 v137, 0xffff0000, v137
	v_fmac_f32_e32 v143, v53, v0
	v_mul_f32_e32 v0, 0xbfb8aa3b, v149
	v_exp_f32_e32 v0, v0
	v_cvt_pk_bf16_f32 v143, v155, v143
	v_cvt_pk_bf16_f32 v144, v156, v144
	v_lshlrev_b32_e32 v149, 16, v136
	v_add_f32_e32 v0, 1.0, v0
	v_rcp_f32_e32 v0, v0
	v_and_b32_e32 v136, 0xffff0000, v136
	v_fmac_f32_e32 v145, v49, v0
	v_lshlrev_b32_e32 v0, 16, v138
	v_mul_f32_e32 v0, 0xbfb8aa3b, v0
	v_exp_f32_e32 v0, v0
	v_cvt_pk_bf16_f32 v145, v157, v145
	global_store_dwordx4 v[146:147], v[142:145], off
	v_and_b32_e32 v138, 0xffff0000, v138
	v_add_f32_e32 v0, 1.0, v0
	v_rcp_f32_e32 v0, v0
	v_lshlrev_b32_e32 v143, 16, v140
	v_lshlrev_b32_e32 v145, 16, v134
	v_and_b32_e32 v140, 0xffff0000, v140
	v_fmac_f32_e32 v145, v42, v0
	v_mul_f32_e32 v0, 0xbfb8aa3b, v143
	v_exp_f32_e32 v0, v0
	v_and_b32_e32 v134, 0xffff0000, v134
	v_lshlrev_b32_e32 v142, 16, v139
	v_lshlrev_b32_e32 v144, 16, v141
	v_add_f32_e32 v0, 1.0, v0
	v_rcp_f32_e32 v0, v0
	v_and_b32_e32 v139, 0xffff0000, v139
	v_and_b32_e32 v141, 0xffff0000, v141
	v_fmac_f32_e32 v149, v38, v0
	v_mul_f32_e32 v0, 0xbfb8aa3b, v138
	v_exp_f32_e32 v0, v0
	s_nop 0
	v_add_f32_e32 v0, 1.0, v0
	v_rcp_f32_e32 v0, v0
	s_nop 0
	v_fmac_f32_e32 v134, v43, v0
	v_mul_f32_e32 v0, 0xbfb8aa3b, v140
	v_exp_f32_e32 v0, v0
	v_cvt_pk_bf16_f32 v134, v145, v134
	s_nop 0
	v_add_f32_e32 v0, 1.0, v0
	v_rcp_f32_e32 v0, v0
	s_nop 0
	v_fmac_f32_e32 v136, v39, v0
	v_mul_f32_e32 v0, 0xbfb8aa3b, v142
	v_exp_f32_e32 v0, v0
	s_nop 0
	v_add_f32_e32 v0, 1.0, v0
	v_rcp_f32_e32 v0, v0
	s_nop 0
	v_fmac_f32_e32 v148, v44, v0
	v_mul_f32_e32 v0, 0xbfb8aa3b, v144
	v_exp_f32_e32 v0, v0
	s_nop 0
	v_add_f32_e32 v0, 1.0, v0
	v_rcp_f32_e32 v0, v0
	s_nop 0
	v_fmac_f32_e32 v150, v40, v0
; __device__ __forceinline__ float sigmoidf_(float g) { return __builtin_amdgcn_rcpf(1.f + __expf(-g)); }
; __device__ __forceinline__ u32x4 pack8(const f32x4& a, const f32x4& b) { u32x4 w; w.x = cvt_pk_bf16(a[0], a[1]); w.y = cvt_pk_bf16(a[2], a[3]); w.z = cvt_pk_bf16(b[0], b[1]); w.w = cvt_pk_bf16(b[2], b[3]); return w; }
; __device__ __forceinline__ void unpack8(const u32x4& w, float (&v)[8]) { v[0] = bf_lo(w.x); v[1] = bf_hi(w.x); v[2] = bf_lo(w.y); v[3] = bf_hi(w.y); v[4] = bf_lo(w.z); v[5] = bf_hi(w.z); v[6] = bf_lo(w.w); v[7] = bf_hi(w.w); }
;     __device__ __forceinline__ void apply(const Ld& d, int row, int c0, int, int, int, const f32x4& a0, const f32x4& b0, const f32x4& a1, const f32x4& b1) const { half(d.g0, row, c0, a0, b0); half(d.g1, row, c0 + 128, a1, b1); }
;     __device__ __forceinline__ void half(const u32x4& gw, const u32x4& pw, int row, int col, const f32x4& a, const f32x4& b) const {
;         float g[8]; unpack8(gw, g); float p[8]; unpack8(pw, p);
;         f32x4 r0, r1;
; #pragma unroll
;         for (int i = 0; i < 4; ++i) { r0[i] = a[i] * sigmoidf_(g[i]) + p[i]; r1[i] = b[i] * sigmoidf_(g[4 + i]) + p[4 + i]; }
;         *(u32x4*)(merged + (size_t)row * 1024 + col) = pack8(r0, r1);
;     }
;     __device__ __forceinline__ void apply(const Ld& d, int row, int c0, int, int, int, const f32x4& a0, const f32x4& b0, const f32x4& a1, const f32x4& b1) const { half(d.g0, d.p0, row, c0, a0, b0); half(d.g1, d.p1, row, c0 + 128, a1, b1); }
	v_mul_f32_e32 v0, 0xbfb8aa3b, v139
	v_exp_f32_e32 v0, v0
	s_nop 0
	v_add_f32_e32 v0, 1.0, v0
	v_rcp_f32_e32 v0, v0
	s_nop 0
	v_fmac_f32_e32 v135, v45, v0
	v_mul_f32_e32 v0, 0xbfb8aa3b, v141
	v_exp_f32_e32 v0, v0
	v_cvt_pk_bf16_f32 v135, v148, v135
	v_cvt_pk_bf16_f32 v136, v149, v136
	s_nop 0
	v_add_f32_e32 v0, 1.0, v0
	v_rcp_f32_e32 v0, v0
	s_nop 0
	v_fmac_f32_e32 v137, v41, v0
	v_add_u32_e32 v0, 0xa0, v166
	v_cvt_pk_bf16_f32 v137, v150, v137
	global_store_dwordx4 v[146:147], v[134:137], off offset:256
	s_nop 1
	v_mad_i64_i32 v[134:135], s[22:23], v0, s29, v[168:169]
	v_lshl_add_u64 v[134:135], v[134:135], 0, v[164:165]
	v_add_co_u32_e32 v136, vcc, s98, v134
	v_add_u32_e32 v0, 0xb0, v166
	s_nop 0
	v_addc_co_u32_e32 v137, vcc, 0, v135, vcc
	global_load_dwordx4 v[154:157], v[136:137], off offset:3072
	global_load_dwordx4 v[150:153], v[136:137], off offset:3328
	global_load_dwordx4 v[158:161], v[134:135], off offset:2048
	global_load_dwordx4 v[170:173], v[134:135], off offset:2304
	v_mad_i64_i32 v[134:135], s[22:23], v0, s29, v[168:169]
	v_lshl_add_u64 v[134:135], v[134:135], 0, v[164:165]
	v_add_co_u32_e32 v136, vcc, s98, v134
	v_add_u32_e32 v164, s0, v239
	s_nop 0
	v_addc_co_u32_e32 v137, vcc, 0, v135, vcc
	global_load_dwordx4 v[146:149], v[136:137], off offset:3072
	global_load_dwordx4 v[138:141], v[136:137], off offset:3328
	global_load_dwordx4 v[142:145], v[134:135], off offset:2048
	s_nop 0
	global_load_dwordx4 v[134:137], v[134:135], off offset:2304
	s_waitcnt vmcnt(0)
	v_lshlrev_b32_e32 v0, 16, v154
	v_mul_f32_e32 v0, 0xbfb8aa3b, v0
	v_exp_f32_e32 v0, v0
	v_lshlrev_b32_e32 v166, 16, v156
	v_lshlrev_b32_e32 v168, 16, v158
	v_and_b32_e32 v154, 0xffff0000, v154
	v_add_f32_e32 v0, 1.0, v0
	v_rcp_f32_e32 v0, v0
	v_lshlrev_b32_e32 v174, 16, v160
	v_and_b32_e32 v156, 0xffff0000, v156
	v_and_b32_e32 v158, 0xffff0000, v158
	v_fmac_f32_e32 v168, v34, v0
	v_mul_f32_e32 v0, 0xbfb8aa3b, v166
	v_exp_f32_e32 v0, v0
	v_lshlrev_b32_e32 v165, 16, v155
	v_and_b32_e32 v160, 0xffff0000, v160
	v_lshlrev_b32_e32 v167, 16, v157
	v_add_f32_e32 v0, 1.0, v0
	v_rcp_f32_e32 v0, v0
	v_lshlrev_b32_e32 v169, 16, v159
	v_and_b32_e32 v155, 0xffff0000, v155
	v_lshlrev_b32_e32 v175, 16, v161
	v_fmac_f32_e32 v174, v30, v0
	v_mul_f32_e32 v0, 0xbfb8aa3b, v154
	v_exp_f32_e32 v0, v0
	v_and_b32_e32 v157, 0xffff0000, v157
	v_and_b32_e32 v159, 0xffff0000, v159
	v_and_b32_e32 v161, 0xffff0000, v161
	v_add_f32_e32 v0, 1.0, v0
	v_rcp_f32_e32 v0, v0
	v_and_b32_e32 v166, 0xffff0000, v172
	v_fmac_f32_e32 v158, v35, v0
	v_mul_f32_e32 v0, 0xbfb8aa3b, v156
	v_exp_f32_e32 v0, v0
	v_cvt_pk_bf16_f32 v154, v168, v158
	v_and_b32_e32 v168, 0xffff0000, v173
	v_add_f32_e32 v0, 1.0, v0
	v_rcp_f32_e32 v0, v0
	s_nop 0
	v_fmac_f32_e32 v160, v31, v0
	v_mul_f32_e32 v0, 0xbfb8aa3b, v165
	v_exp_f32_e32 v0, v0
	v_ashrrev_i32_e32 v165, 31, v164
	v_add_f32_e32 v0, 1.0, v0
	v_rcp_f32_e32 v0, v0
	s_nop 0
	v_fmac_f32_e32 v169, v36, v0
	v_mul_f32_e32 v0, 0xbfb8aa3b, v167
	v_exp_f32_e32 v0, v0
	v_lshlrev_b32_e32 v167, 16, v173
	v_add_f32_e32 v0, 1.0, v0
	v_rcp_f32_e32 v0, v0
	s_nop 0
	v_fmac_f32_e32 v175, v32, v0
	v_mul_f32_e32 v0, 0xbfb8aa3b, v155
	v_exp_f32_e32 v0, v0
	s_nop 0
	v_add_f32_e32 v0, 1.0, v0
	v_rcp_f32_e32 v0, v0
	s_nop 0
	v_fmac_f32_e32 v159, v37, v0
	v_mul_f32_e32 v0, 0xbfb8aa3b, v157
	v_exp_f32_e32 v0, v0
	v_cvt_pk_bf16_f32 v155, v169, v159
	v_lshlrev_b64 v[158:159], 11, v[164:165]
	v_cvt_pk_bf16_f32 v156, v174, v160
	v_add_f32_e32 v0, 1.0, v0
	v_rcp_f32_e32 v0, v0
	v_lshl_add_u64 v[158:159], v[162:163], 0, v[158:159]
	v_lshlrev_b32_e32 v165, 16, v172
	v_and_b32_e32 v160, 0xffff0000, v170
	v_fmac_f32_e32 v161, v33, v0
	v_lshlrev_b32_e32 v0, 16, v150
	v_mul_f32_e32 v0, 0xbfb8aa3b, v0
	v_exp_f32_e32 v0, v0
	v_cvt_pk_bf16_f32 v157, v175, v161
	global_store_dwordx4 v[158:159], v[154:157], off
	v_and_b32_e32 v150, 0xffff0000, v150
	v_add_f32_e32 v0, 1.0, v0
	v_rcp_f32_e32 v0, v0
	v_lshlrev_b32_e32 v155, 16, v152
	v_lshlrev_b32_e32 v157, 16, v170
	v_and_b32_e32 v152, 0xffff0000, v152
	v_fmac_f32_e32 v157, v26, v0
	v_mul_f32_e32 v0, 0xbfb8aa3b, v155
	v_exp_f32_e32 v0, v0
	v_lshlrev_b32_e32 v154, 16, v151
	v_lshlrev_b32_e32 v156, 16, v153
	v_lshlrev_b32_e32 v161, 16, v171
	v_add_f32_e32 v0, 1.0, v0
	v_rcp_f32_e32 v0, v0
	v_and_b32_e32 v151, 0xffff0000, v151
	v_and_b32_e32 v153, 0xffff0000, v153
	v_and_b32_e32 v164, 0xffff0000, v171
	v_fmac_f32_e32 v165, v22, v0
	v_mul_f32_e32 v0, 0xbfb8aa3b, v150
	v_exp_f32_e32 v0, v0
	v_lshlrev_b32_e32 v155, 16, v143
	v_and_b32_e32 v143, 0xffff0000, v143
	v_add_f32_e32 v0, 1.0, v0
	v_rcp_f32_e32 v0, v0
	s_nop 0
	v_fmac_f32_e32 v160, v27, v0
	v_mul_f32_e32 v0, 0xbfb8aa3b, v152
	v_exp_f32_e32 v0, v0
	v_cvt_pk_bf16_f32 v150, v157, v160
	v_lshlrev_b32_e32 v157, 16, v145
	v_and_b32_e32 v145, 0xffff0000, v145
; __device__ __forceinline__ float sigmoidf_(float g) { return __builtin_amdgcn_rcpf(1.f + __expf(-g)); }
; __device__ __forceinline__ u32x4 pack8(const f32x4& a, const f32x4& b) { u32x4 w; w.x = cvt_pk_bf16(a[0], a[1]); w.y = cvt_pk_bf16(a[2], a[3]); w.z = cvt_pk_bf16(b[0], b[1]); w.w = cvt_pk_bf16(b[2], b[3]); return w; }
; __device__ __forceinline__ void unpack8(const u32x4& w, float (&v)[8]) { v[0] = bf_lo(w.x); v[1] = bf_hi(w.x); v[2] = bf_lo(w.y); v[3] = bf_hi(w.y); v[4] = bf_lo(w.z); v[5] = bf_hi(w.z); v[6] = bf_lo(w.w); v[7] = bf_hi(w.w); }
;     __device__ __forceinline__ void apply(const Ld& d, int row, int c0, int, int, int, const f32x4& a0, const f32x4& b0, const f32x4& a1, const f32x4& b1) const { half(d.g0, row, c0, a0, b0); half(d.g1, row, c0 + 128, a1, b1); }
;     __device__ __forceinline__ void half(const u32x4& gw, const u32x4& pw, int row, int col, const f32x4& a, const f32x4& b) const {
;         float g[8]; unpack8(gw, g); float p[8]; unpack8(pw, p);
;         f32x4 r0, r1;
; #pragma unroll
;         for (int i = 0; i < 4; ++i) { r0[i] = a[i] * sigmoidf_(g[i]) + p[i]; r1[i] = b[i] * sigmoidf_(g[4 + i]) + p[4 + i]; }
;         *(u32x4*)(merged + (size_t)row * 1024 + col) = pack8(r0, r1);
;     }
;     __device__ __forceinline__ void apply(const Ld& d, int row, int c0, int, int, int, const f32x4& a0, const f32x4& b0, const f32x4& a1, const f32x4& b1) const { half(d.g0, d.p0, row, c0, a0, b0); half(d.g1, d.p1, row, c0 + 128, a1, b1); }
	v_add_f32_e32 v0, 1.0, v0
	v_rcp_f32_e32 v0, v0
	s_nop 0
	v_fmac_f32_e32 v166, v23, v0
	v_mul_f32_e32 v0, 0xbfb8aa3b, v154
	v_exp_f32_e32 v0, v0
	v_lshlrev_b32_e32 v154, 16, v142
	v_and_b32_e32 v142, 0xffff0000, v142
	v_add_f32_e32 v0, 1.0, v0
	v_rcp_f32_e32 v0, v0
	s_nop 0
	v_fmac_f32_e32 v161, v28, v0
	v_mul_f32_e32 v0, 0xbfb8aa3b, v156
	v_exp_f32_e32 v0, v0
	v_lshlrev_b32_e32 v156, 16, v144
	v_and_b32_e32 v144, 0xffff0000, v144
	v_add_f32_e32 v0, 1.0, v0
	v_rcp_f32_e32 v0, v0
	s_nop 0
	v_fmac_f32_e32 v167, v24, v0
	v_mul_f32_e32 v0, 0xbfb8aa3b, v151
	v_exp_f32_e32 v0, v0
	s_nop 0
	v_add_f32_e32 v0, 1.0, v0
	v_rcp_f32_e32 v0, v0
	s_nop 0
	v_fmac_f32_e32 v164, v29, v0
	v_mul_f32_e32 v0, 0xbfb8aa3b, v153
	v_exp_f32_e32 v0, v0
	v_cvt_pk_bf16_f32 v151, v161, v164
	v_cvt_pk_bf16_f32 v152, v165, v166
	s_nop 0
	v_add_f32_e32 v0, 1.0, v0
	v_rcp_f32_e32 v0, v0
	s_nop 0
	v_fmac_f32_e32 v168, v25, v0
	v_lshlrev_b32_e32 v0, 16, v146
	v_mul_f32_e32 v0, 0xbfb8aa3b, v0
	v_exp_f32_e32 v0, v0
	v_cvt_pk_bf16_f32 v153, v167, v168
	global_store_dwordx4 v[158:159], v[150:153], off offset:256
	v_and_b32_e32 v146, 0xffff0000, v146
	v_add_f32_e32 v0, 1.0, v0
	v_rcp_f32_e32 v0, v0
	v_lshlrev_b32_e32 v152, 16, v148
	v_and_b32_e32 v148, 0xffff0000, v148
	v_lshlrev_b32_e32 v151, 16, v147
	v_fmac_f32_e32 v154, v18, v0
	v_mul_f32_e32 v0, 0xbfb8aa3b, v152
	v_exp_f32_e32 v0, v0
	v_lshlrev_b32_e32 v153, 16, v149
	v_and_b32_e32 v147, 0xffff0000, v147
	v_and_b32_e32 v149, 0xffff0000, v149
	v_add_f32_e32 v0, 1.0, v0
	v_rcp_f32_e32 v0, v0
	v_add_u32_e32 v150, s0, v240
	v_fmac_f32_e32 v156, v10, v0
	v_mul_f32_e32 v0, 0xbfb8aa3b, v146
	v_exp_f32_e32 v0, v0
	s_nop 0
	v_add_f32_e32 v0, 1.0, v0
	v_rcp_f32_e32 v0, v0
	s_nop 0
	v_fmac_f32_e32 v142, v19, v0
	v_mul_f32_e32 v0, 0xbfb8aa3b, v148
	v_exp_f32_e32 v0, v0
	v_cvt_pk_bf16_f32 v142, v154, v142
	v_lshlrev_b32_e32 v148, 16, v135
	v_and_b32_e32 v135, 0xffff0000, v135
	v_add_f32_e32 v0, 1.0, v0
	v_rcp_f32_e32 v0, v0
	s_nop 0
	v_fmac_f32_e32 v144, v11, v0
	v_mul_f32_e32 v0, 0xbfb8aa3b, v151
	v_exp_f32_e32 v0, v0
	v_ashrrev_i32_e32 v151, 31, v150
	v_add_f32_e32 v0, 1.0, v0
	v_rcp_f32_e32 v0, v0
	s_nop 0
	v_fmac_f32_e32 v155, v20, v0
	v_mul_f32_e32 v0, 0xbfb8aa3b, v153
	v_exp_f32_e32 v0, v0
	s_nop 0
	v_add_f32_e32 v0, 1.0, v0
	v_rcp_f32_e32 v0, v0
	s_nop 0
	v_fmac_f32_e32 v157, v12, v0
	v_mul_f32_e32 v0, 0xbfb8aa3b, v147
	v_exp_f32_e32 v0, v0
	v_lshlrev_b64 v[146:147], 11, v[150:151]
	v_lshl_add_u64 v[146:147], v[162:163], 0, v[146:147]
	v_lshlrev_b32_e32 v150, 16, v137
	v_add_f32_e32 v0, 1.0, v0
	v_rcp_f32_e32 v0, v0
	v_and_b32_e32 v137, 0xffff0000, v137
	v_fmac_f32_e32 v143, v21, v0
	v_mul_f32_e32 v0, 0xbfb8aa3b, v149
	v_exp_f32_e32 v0, v0
	v_cvt_pk_bf16_f32 v143, v155, v143
	v_cvt_pk_bf16_f32 v144, v156, v144
	v_lshlrev_b32_e32 v149, 16, v136
	v_add_f32_e32 v0, 1.0, v0
	v_rcp_f32_e32 v0, v0
	v_and_b32_e32 v136, 0xffff0000, v136
	v_fmac_f32_e32 v145, v13, v0
	v_lshlrev_b32_e32 v0, 16, v138
	v_mul_f32_e32 v0, 0xbfb8aa3b, v0
	v_exp_f32_e32 v0, v0
	v_cvt_pk_bf16_f32 v145, v157, v145
	global_store_dwordx4 v[146:147], v[142:145], off
	v_and_b32_e32 v138, 0xffff0000, v138
	v_add_f32_e32 v0, 1.0, v0
	v_rcp_f32_e32 v0, v0
	v_lshlrev_b32_e32 v143, 16, v140
	v_lshlrev_b32_e32 v145, 16, v134
	v_and_b32_e32 v140, 0xffff0000, v140
	v_fmac_f32_e32 v145, v6, v0
	v_mul_f32_e32 v0, 0xbfb8aa3b, v143
	v_exp_f32_e32 v0, v0
	v_and_b32_e32 v134, 0xffff0000, v134
	v_lshlrev_b32_e32 v142, 16, v139
	v_lshlrev_b32_e32 v144, 16, v141
	v_add_f32_e32 v0, 1.0, v0
	v_rcp_f32_e32 v0, v0
	v_and_b32_e32 v139, 0xffff0000, v139
	v_and_b32_e32 v141, 0xffff0000, v141
	v_fmac_f32_e32 v149, v2, v0
	v_mul_f32_e32 v0, 0xbfb8aa3b, v138
	v_exp_f32_e32 v0, v0
	s_nop 0
	v_add_f32_e32 v0, 1.0, v0
	v_rcp_f32_e32 v0, v0
	s_nop 0
	v_fmac_f32_e32 v134, v7, v0
	v_mul_f32_e32 v0, 0xbfb8aa3b, v140
	v_exp_f32_e32 v0, v0
	v_cvt_pk_bf16_f32 v134, v145, v134
	s_nop 0
	v_add_f32_e32 v0, 1.0, v0
	v_rcp_f32_e32 v0, v0
	s_nop 0
	v_fmac_f32_e32 v136, v3, v0
	v_mul_f32_e32 v0, 0xbfb8aa3b, v142
	v_exp_f32_e32 v0, v0
	s_nop 0
	v_add_f32_e32 v0, 1.0, v0
	v_rcp_f32_e32 v0, v0
	s_nop 0
	v_fmac_f32_e32 v148, v8, v0
	v_mul_f32_e32 v0, 0xbfb8aa3b, v144
	v_exp_f32_e32 v0, v0
	s_nop 0
	v_add_f32_e32 v0, 1.0, v0
	v_rcp_f32_e32 v0, v0
	s_nop 0
	v_fmac_f32_e32 v150, v4, v0
	v_mul_f32_e32 v0, 0xbfb8aa3b, v139
	v_exp_f32_e32 v0, v0
	s_nop 0
	v_add_f32_e32 v0, 1.0, v0
	v_rcp_f32_e32 v0, v0
	s_nop 0
	v_fmac_f32_e32 v135, v9, v0
	v_mul_f32_e32 v0, 0xbfb8aa3b, v141
	v_exp_f32_e32 v0, v0
	v_cvt_pk_bf16_f32 v135, v148, v135
	v_cvt_pk_bf16_f32 v136, v149, v136
	s_nop 0
	v_add_f32_e32 v0, 1.0, v0
	v_rcp_f32_e32 v0, v0
	s_nop 0
	v_fmac_f32_e32 v137, v5, v0
	v_cvt_pk_bf16_f32 v137, v150, v137
	global_store_dwordx4 v[146:147], v[134:137], off offset:256
